# sample indexer key-block loop: prefetch depth 2 (two landing buffers chosen by iteration parity, block 1 requested in the preheader, latch waits with vmcnt(8))
# baseline (speedup 1.0000x reference)
.LBB0_1079:
	v_readlane_b32 s0, v252, 8
	v_readlane_b32 s1, v252, 9
	s_andn2_b64 vcc, exec, s[0:1]
	s_cbranch_vccnz .LBB0_1110
	v_or_b32_e32 v36, v36, v194
	v_readlane_b32 s6, v252, 35
	v_readlane_b32 s7, v252, 36
	v_lshlrev_b64 v[234:235], 2, v[34:35]
	s_nop 1
	v_lshl_add_u64 v[234:235], s[6:7], 0, v[234:235]
	global_load_dword v202, v[234:235], off
	global_load_dword v203, v[234:235], off offset:8
	global_load_dword v204, v[234:235], off offset:16
	global_load_dword v205, v[234:235], off offset:24
	global_load_dword v206, v[234:235], off offset:32
	global_load_dword v207, v[234:235], off offset:40
	global_load_dword v208, v[234:235], off offset:48
	s_waitcnt vmcnt(0)
	v_mul_f32_e32 v186, 0x3d3504f3, v37
	v_ashrrev_i32_e32 v37, 31, v36
	v_lshlrev_b64 v[36:37], 7, v[36:37]
	v_lshl_add_u64 v[188:189], v[106:107], 0, v[36:37]
	v_add_u32_e32 v36, v195, v1
	v_mad_i64_i32 v[190:191], s[0:1], v36, s59, v[182:183]
	v_readlane_b32 s0, v252, 35
	v_lshlrev_b64 v[34:35], 2, v[34:35]
	v_readlane_b32 s1, v252, 36
	v_mov_b32_e32 v187, v186
	s_mov_b32 s10, s90
	v_lshl_add_u64 v[192:193], s[0:1], 0, v[34:35]
	s_mov_b32 s11, s88
	v_readlane_b32 s44, v251, 14
	v_readlane_b32 s45, v251, 15
	s_nop 1
	v_mov_b32_e32 v34, v202
	v_mov_b32_e32 v202, v203
	v_mov_b32_e32 v203, v204
	v_mov_b32_e32 v204, v205
	v_mov_b32_e32 v205, v206
	v_mov_b32_e32 v206, v207
	v_mov_b32_e32 v207, v208
	s_and_b32 s0, s10, 0x1800
	v_or_b32_e32 v35, s0, v197
	v_lshlrev_b32_e32 v98, 2, v35
	v_mov_b32_e32 v185, v99
	v_ashrrev_i32_e32 v35, 31, v34
	v_lshlrev_b64 v[34:35], 15, v[34:35]
	v_lshl_add_u64 v[34:35], s[44:45], 0, v[34:35]
	v_lshl_add_u64 v[34:35], v[34:35], 0, v[98:99]
	v_lshl_add_u64 v[62:63], v[34:35], 0, v[184:185]
	global_load_dwordx4 v[34:37], v[62:63], off offset:16
	global_load_dwordx4 v[38:41], v[62:63], off
	global_load_dwordx4 v[42:45], v[62:63], off offset:80
	global_load_dwordx4 v[46:49], v[62:63], off offset:64
	global_load_dwordx4 v[50:53], v[62:63], off offset:144
	global_load_dwordx4 v[54:57], v[62:63], off offset:128
	global_load_dwordx4 v[58:61], v[62:63], off offset:208
	s_nop 0
	global_load_dwordx4 v[62:65], v[62:63], off offset:192
	s_branch .LBB0_1082
.LBB0_1081:
	s_or_b64 exec, exec, s[0:1]
	s_cmp_gt_u32 s11, 47
	s_cbranch_scc1 .Lis_w0
	s_waitcnt vmcnt(8)
	s_branch .Lis_wd

.Lis_wd:
	s_add_i32 s6, s11, 8
	s_addk_i32 s10, 0x4000
	s_mov_b64 s[0:1], 0x400
	s_nop 0
	v_lshl_add_u64 v[190:191], v[190:191], 0, s[0:1]
	v_lshl_add_u64 v[192:193], v[192:193], 0, 8
	s_bitcmp1_b32 s11, 3
	s_cbranch_scc1 .Lis_copyB
	v_mov_b64_e32 v[2:3], v[58:59]
	v_mov_b64_e32 v[4:5], v[60:61]
	v_mov_b64_e32 v[66:67], v[62:63]
	v_mov_b64_e32 v[68:69], v[64:65]
	v_mov_b64_e32 v[6:7], v[50:51]
	v_mov_b64_e32 v[8:9], v[52:53]
	v_mov_b64_e32 v[70:71], v[54:55]
	v_mov_b64_e32 v[72:73], v[56:57]
	v_mov_b64_e32 v[10:11], v[42:43]
	v_mov_b64_e32 v[12:13], v[44:45]
	v_mov_b64_e32 v[74:75], v[46:47]
	v_mov_b64_e32 v[76:77], v[48:49]
	v_mov_b64_e32 v[14:15], v[34:35]
	v_mov_b64_e32 v[16:17], v[36:37]
	v_mov_b64_e32 v[78:79], v[38:39]
	v_mov_b64_e32 v[80:81], v[40:41]
	s_branch .Lis_cd
.Lis_copyB:
	v_mov_b64_e32 v[2:3], v[234:235]
	v_mov_b64_e32 v[4:5], v[236:237]
	v_mov_b64_e32 v[66:67], v[238:239]
	v_mov_b64_e32 v[68:69], v[240:241]
	v_mov_b64_e32 v[6:7], v[226:227]
	v_mov_b64_e32 v[8:9], v[228:229]
	v_mov_b64_e32 v[70:71], v[230:231]
	v_mov_b64_e32 v[72:73], v[232:233]
	v_mov_b64_e32 v[10:11], v[218:219]
	v_mov_b64_e32 v[12:13], v[220:221]
	v_mov_b64_e32 v[74:75], v[222:223]
	v_mov_b64_e32 v[76:77], v[224:225]
	v_mov_b64_e32 v[14:15], v[210:211]
	v_mov_b64_e32 v[16:17], v[212:213]
	v_mov_b64_e32 v[78:79], v[214:215]
	v_mov_b64_e32 v[80:81], v[216:217]
.Lis_cd:
	s_cmp_gt_u32 s11, 56
	s_mov_b32 s11, s6
	s_cbranch_scc1 .LBB0_1110
.LBB0_1082:
	s_cmp_gt_u32 s11, 55
	s_cbranch_scc1 .LBB0_1084
	v_readlane_b32 s36, v251, 6
	v_readlane_b32 s44, v251, 14
	v_readlane_b32 s45, v251, 15
	v_readlane_b32 s37, v251, 7
	v_readlane_b32 s38, v251, 8
	v_readlane_b32 s39, v251, 9
	v_readlane_b32 s40, v251, 10
	v_readlane_b32 s41, v251, 11
	v_readlane_b32 s42, v251, 12
	v_readlane_b32 s43, v251, 13
	v_readlane_b32 s46, v251, 16
	v_readlane_b32 s47, v251, 17
	v_readlane_b32 s48, v251, 18
	v_readlane_b32 s49, v251, 19
	v_readlane_b32 s50, v251, 20
	v_readlane_b32 s51, v251, 21
	s_cmp_gt_u32 s11, 47
	s_cbranch_scc1 .LBB0_1084
	s_bitcmp1_b32 s11, 3
	s_cbranch_scc1 .Lis_issueA
	v_mov_b32_e32 v210, v202
	v_mov_b32_e32 v202, v203
	v_mov_b32_e32 v203, v204
	v_mov_b32_e32 v204, v205
	v_mov_b32_e32 v205, v206
	v_mov_b32_e32 v206, v207
	v_mov_b32_e32 v207, v208
	s_add_i32 s0, s10, 0x4000
	s_and_b32 s0, s0, 0x1800
	v_or_b32_e32 v211, s0, v197
	v_lshlrev_b32_e32 v98, 2, v211
	v_mov_b32_e32 v185, v99
	v_ashrrev_i32_e32 v211, 31, v210
	v_lshlrev_b64 v[210:211], 15, v[210:211]
	v_lshl_add_u64 v[210:211], s[44:45], 0, v[210:211]
	v_lshl_add_u64 v[210:211], v[210:211], 0, v[98:99]
	v_lshl_add_u64 v[238:239], v[210:211], 0, v[184:185]
	global_load_dwordx4 v[210:213], v[238:239], off offset:16
	global_load_dwordx4 v[214:217], v[238:239], off
	global_load_dwordx4 v[218:221], v[238:239], off offset:80
	global_load_dwordx4 v[222:225], v[238:239], off offset:64
	global_load_dwordx4 v[226:229], v[238:239], off offset:144
	global_load_dwordx4 v[230:233], v[238:239], off offset:128
	global_load_dwordx4 v[234:237], v[238:239], off offset:208
	s_nop 0
	global_load_dwordx4 v[238:241], v[238:239], off offset:192
	s_branch .LBB0_1084
.Lis_issueA:
	v_mov_b32_e32 v34, v202
	v_mov_b32_e32 v202, v203
	v_mov_b32_e32 v203, v204
	v_mov_b32_e32 v204, v205
	v_mov_b32_e32 v205, v206
	v_mov_b32_e32 v206, v207
	v_mov_b32_e32 v207, v208
	s_add_i32 s0, s10, 0x4000
	s_and_b32 s0, s0, 0x1800
	v_or_b32_e32 v35, s0, v197
	v_lshlrev_b32_e32 v98, 2, v35
	v_mov_b32_e32 v185, v99
	v_ashrrev_i32_e32 v35, 31, v34
	v_lshlrev_b64 v[34:35], 15, v[34:35]
	v_lshl_add_u64 v[34:35], s[44:45], 0, v[34:35]
	v_lshl_add_u64 v[34:35], v[34:35], 0, v[98:99]
	v_lshl_add_u64 v[62:63], v[34:35], 0, v[184:185]
	global_load_dwordx4 v[34:37], v[62:63], off offset:16
	global_load_dwordx4 v[38:41], v[62:63], off
	global_load_dwordx4 v[42:45], v[62:63], off offset:80
	global_load_dwordx4 v[46:49], v[62:63], off offset:64
	global_load_dwordx4 v[50:53], v[62:63], off offset:144
	global_load_dwordx4 v[54:57], v[62:63], off offset:128
	global_load_dwordx4 v[58:61], v[62:63], off offset:208
	s_nop 0
	global_load_dwordx4 v[62:65], v[62:63], off offset:192
